# FFN-down epilogue: 16 residual loads per tile issued together
# baseline (speedup 1.0000x reference)
.LBB0_1381:
	s_andn2_b64 vcc, exec, s[44:45]
	s_movk_i32 s77, 0xfff
	s_cbranch_vccnz .LBB0_1383
	s_lshl_b32 s4, s70, 8
	v_lshl_add_u32 v156, s68, 8, v137
	s_ashr_i32 s5, s4, 31
	v_ashrrev_i32_e32 v157, 31, v156
	v_mov_b32_e32 v155, s5
	v_or_b32_e32 v154, s4, v136
	v_lshlrev_b64 v[160:161], 10, v[156:157]
	v_lshl_add_u64 v[160:161], v[160:161], 0, v[154:155]
	v_lshl_add_u64 v[164:165], v[160:161], 1, s[38:39]
	global_load_dwordx4 v[172:175], v[164:165], off
	global_load_dwordx4 v[176:179], v[164:165], off offset:256
	s_mov_b64 s[12:13], 0x8000
	v_lshl_add_u64 v[248:249], v[164:165], 0, s[12:13]
	global_load_dwordx4 v[180:183], v[248:249], off
	global_load_dwordx4 v[184:187], v[248:249], off offset:256
	s_mov_b64 s[12:13], 0x10000
	v_lshl_add_u64 v[248:249], v[164:165], 0, s[12:13]
	global_load_dwordx4 v[188:191], v[248:249], off
	global_load_dwordx4 v[204:207], v[248:249], off offset:256
	s_mov_b64 s[12:13], 0x18000
	v_lshl_add_u64 v[248:249], v[164:165], 0, s[12:13]
	global_load_dwordx4 v[208:211], v[248:249], off
	global_load_dwordx4 v[212:215], v[248:249], off offset:256
	s_mov_b64 s[12:13], 0x40000
	v_lshl_add_u64 v[248:249], v[164:165], 0, s[12:13]
	global_load_dwordx4 v[216:219], v[248:249], off
	global_load_dwordx4 v[220:223], v[248:249], off offset:256
	s_mov_b64 s[12:13], 0x48000
	v_lshl_add_u64 v[248:249], v[164:165], 0, s[12:13]
	global_load_dwordx4 v[224:227], v[248:249], off
	global_load_dwordx4 v[228:231], v[248:249], off offset:256
	s_mov_b64 s[12:13], 0x50000
	v_lshl_add_u64 v[248:249], v[164:165], 0, s[12:13]
	global_load_dwordx4 v[232:235], v[248:249], off
	global_load_dwordx4 v[236:239], v[248:249], off offset:256
	s_mov_b64 s[12:13], 0x58000
	v_lshl_add_u64 v[248:249], v[164:165], 0, s[12:13]
	global_load_dwordx4 v[240:243], v[248:249], off
	global_load_dwordx4 v[244:247], v[248:249], off offset:256
	s_waitcnt vmcnt(14)
	v_mov_b64_e32 v[160:161], v[172:173]
	v_mov_b64_e32 v[162:163], v[174:175]
	s_nop 0
	v_lshlrev_b32_e32 v166, 16, v162
	v_and_b32_e32 v167, 0xffff0000, v162
	v_lshlrev_b32_e32 v162, 16, v163
	v_and_b32_e32 v163, 0xffff0000, v163
	v_lshlrev_b32_e32 v168, 16, v160
	v_and_b32_e32 v169, 0xffff0000, v160
	v_lshlrev_b32_e32 v160, 16, v161
	v_and_b32_e32 v161, 0xffff0000, v161
	v_pk_add_f32 v[128:129], v[128:129], v[160:161]
	v_pk_add_f32 v[126:127], v[126:127], v[168:169]
	v_pk_add_f32 v[124:125], v[124:125], v[162:163]
	v_pk_add_f32 v[122:123], v[122:123], v[166:167]
	v_cvt_pk_bf16_f32 v126, v126, v127
	v_cvt_pk_bf16_f32 v127, v128, v129
	v_cvt_pk_bf16_f32 v128, v122, v123
	v_cvt_pk_bf16_f32 v129, v124, v125
	s_waitcnt vmcnt(14)
	v_mov_b64_e32 v[122:123], v[176:177]
	v_mov_b64_e32 v[124:125], v[178:179]
	s_nop 0
	global_store_dwordx4 v[164:165], v[126:129], off
	s_nop 0
	s_nop 0
	v_lshlrev_b32_e32 v126, 16, v124
	v_and_b32_e32 v127, 0xffff0000, v124
	v_lshlrev_b32_e32 v128, 16, v122
	v_and_b32_e32 v129, 0xffff0000, v122
	v_lshlrev_b32_e32 v122, 16, v123
	v_and_b32_e32 v123, 0xffff0000, v123
	v_pk_add_f32 v[120:121], v[120:121], v[122:123]
	v_pk_add_f32 v[118:119], v[118:119], v[128:129]
	v_pk_add_f32 v[114:115], v[114:115], v[126:127]
	v_cvt_pk_bf16_f32 v118, v118, v119
	v_cvt_pk_bf16_f32 v119, v120, v121
	v_cvt_pk_bf16_f32 v120, v114, v115
	v_or_b32_e32 v114, 16, v156
	v_lshlrev_b32_e32 v124, 16, v125
	v_and_b32_e32 v125, 0xffff0000, v125
	v_ashrrev_i32_e32 v115, 31, v114
	v_pk_add_f32 v[116:117], v[116:117], v[124:125]
	v_lshlrev_b64 v[114:115], 10, v[114:115]
	v_cvt_pk_bf16_f32 v121, v116, v117
	v_lshl_add_u64 v[114:115], v[114:115], 0, v[154:155]
	global_store_dwordx4 v[164:165], v[118:121], off offset:256
	v_lshl_add_u64 v[114:115], v[114:115], 1, s[38:39]
	s_waitcnt vmcnt(14)
	v_mov_b64_e32 v[116:117], v[180:181]
	v_mov_b64_e32 v[118:119], v[182:183]
	s_nop 0
	v_lshlrev_b32_e32 v120, 16, v118
	v_and_b32_e32 v121, 0xffff0000, v118
	v_lshlrev_b32_e32 v118, 16, v119
	v_and_b32_e32 v119, 0xffff0000, v119
	v_lshlrev_b32_e32 v122, 16, v116
	v_and_b32_e32 v123, 0xffff0000, v116
	v_lshlrev_b32_e32 v116, 16, v117
	v_and_b32_e32 v117, 0xffff0000, v117
	v_pk_add_f32 v[112:113], v[112:113], v[116:117]
	v_pk_add_f32 v[110:111], v[110:111], v[122:123]
	v_pk_add_f32 v[108:109], v[108:109], v[118:119]
	v_pk_add_f32 v[106:107], v[106:107], v[120:121]
	v_cvt_pk_bf16_f32 v110, v110, v111
	v_cvt_pk_bf16_f32 v111, v112, v113
	v_cvt_pk_bf16_f32 v112, v106, v107
	v_cvt_pk_bf16_f32 v113, v108, v109
	s_waitcnt vmcnt(14)
	v_mov_b64_e32 v[106:107], v[184:185]
	v_mov_b64_e32 v[108:109], v[186:187]
	s_nop 0
	global_store_dwordx4 v[114:115], v[110:113], off
	s_nop 0
	s_nop 0
	v_lshlrev_b32_e32 v110, 16, v108
	v_and_b32_e32 v111, 0xffff0000, v108
	v_lshlrev_b32_e32 v112, 16, v106
	v_and_b32_e32 v113, 0xffff0000, v106
	v_lshlrev_b32_e32 v106, 16, v107
	v_and_b32_e32 v107, 0xffff0000, v107
	v_pk_add_f32 v[104:105], v[104:105], v[106:107]
	v_pk_add_f32 v[102:103], v[102:103], v[112:113]
	v_pk_add_f32 v[98:99], v[98:99], v[110:111]
	v_cvt_pk_bf16_f32 v102, v102, v103
	v_cvt_pk_bf16_f32 v103, v104, v105
	v_cvt_pk_bf16_f32 v104, v98, v99
	v_or_b32_e32 v98, 32, v156
	v_lshlrev_b32_e32 v108, 16, v109
	v_and_b32_e32 v109, 0xffff0000, v109
	v_ashrrev_i32_e32 v99, 31, v98
	v_pk_add_f32 v[100:101], v[100:101], v[108:109]
	v_lshlrev_b64 v[98:99], 10, v[98:99]
	v_cvt_pk_bf16_f32 v105, v100, v101
	v_lshl_add_u64 v[98:99], v[98:99], 0, v[154:155]
	global_store_dwordx4 v[114:115], v[102:105], off offset:256
	v_lshl_add_u64 v[98:99], v[98:99], 1, s[38:39]
	s_waitcnt vmcnt(14)
	v_mov_b64_e32 v[100:101], v[188:189]
	v_mov_b64_e32 v[102:103], v[190:191]
	s_nop 0
	v_lshlrev_b32_e32 v104, 16, v102
	v_and_b32_e32 v105, 0xffff0000, v102
	v_lshlrev_b32_e32 v102, 16, v103
	v_and_b32_e32 v103, 0xffff0000, v103
	v_lshlrev_b32_e32 v106, 16, v100
	v_and_b32_e32 v107, 0xffff0000, v100
	v_lshlrev_b32_e32 v100, 16, v101
	v_and_b32_e32 v101, 0xffff0000, v101
	v_pk_add_f32 v[96:97], v[96:97], v[100:101]
	v_pk_add_f32 v[94:95], v[94:95], v[106:107]
	v_pk_add_f32 v[92:93], v[92:93], v[102:103]
	v_pk_add_f32 v[90:91], v[90:91], v[104:105]
	v_cvt_pk_bf16_f32 v94, v94, v95
	v_cvt_pk_bf16_f32 v95, v96, v97
	v_cvt_pk_bf16_f32 v96, v90, v91
	v_cvt_pk_bf16_f32 v97, v92, v93
	s_waitcnt vmcnt(14)
	v_mov_b64_e32 v[90:91], v[204:205]
	v_mov_b64_e32 v[92:93], v[206:207]
	s_nop 0
	global_store_dwordx4 v[98:99], v[94:97], off
	s_nop 0
	s_nop 0
	v_lshlrev_b32_e32 v94, 16, v92
	v_and_b32_e32 v95, 0xffff0000, v92
	v_lshlrev_b32_e32 v96, 16, v90
	v_and_b32_e32 v97, 0xffff0000, v90
	v_lshlrev_b32_e32 v90, 16, v91
	v_and_b32_e32 v91, 0xffff0000, v91
	v_pk_add_f32 v[88:89], v[88:89], v[90:91]
	v_pk_add_f32 v[86:87], v[86:87], v[96:97]
	v_pk_add_f32 v[82:83], v[82:83], v[94:95]
	v_cvt_pk_bf16_f32 v86, v86, v87
	v_cvt_pk_bf16_f32 v87, v88, v89
	v_cvt_pk_bf16_f32 v88, v82, v83
	v_or_b32_e32 v82, 48, v156
	v_lshlrev_b32_e32 v92, 16, v93
	v_and_b32_e32 v93, 0xffff0000, v93
	v_ashrrev_i32_e32 v83, 31, v82
	v_pk_add_f32 v[84:85], v[84:85], v[92:93]
	v_lshlrev_b64 v[82:83], 10, v[82:83]
	v_cvt_pk_bf16_f32 v89, v84, v85
	v_lshl_add_u64 v[82:83], v[82:83], 0, v[154:155]
	global_store_dwordx4 v[98:99], v[86:89], off offset:256
	v_lshl_add_u64 v[82:83], v[82:83], 1, s[38:39]
	s_waitcnt vmcnt(14)
	v_mov_b64_e32 v[84:85], v[208:209]
	v_mov_b64_e32 v[86:87], v[210:211]
	s_nop 0
	v_lshlrev_b32_e32 v88, 16, v86
	v_and_b32_e32 v89, 0xffff0000, v86
	v_lshlrev_b32_e32 v86, 16, v87
	v_and_b32_e32 v87, 0xffff0000, v87
	v_lshlrev_b32_e32 v90, 16, v84
	v_and_b32_e32 v91, 0xffff0000, v84
	v_lshlrev_b32_e32 v84, 16, v85
	v_and_b32_e32 v85, 0xffff0000, v85
	v_pk_add_f32 v[80:81], v[80:81], v[84:85]
	v_pk_add_f32 v[78:79], v[78:79], v[90:91]
	v_pk_add_f32 v[76:77], v[76:77], v[86:87]
	v_pk_add_f32 v[74:75], v[74:75], v[88:89]
	v_cvt_pk_bf16_f32 v78, v78, v79
	v_cvt_pk_bf16_f32 v79, v80, v81
	v_cvt_pk_bf16_f32 v80, v74, v75
	v_cvt_pk_bf16_f32 v81, v76, v77
	s_waitcnt vmcnt(14)
	v_mov_b64_e32 v[74:75], v[212:213]
	v_mov_b64_e32 v[76:77], v[214:215]
	s_nop 0
	global_store_dwordx4 v[82:83], v[78:81], off
	s_nop 0
	s_nop 0
	v_lshlrev_b32_e32 v78, 16, v76
	v_and_b32_e32 v79, 0xffff0000, v76
	v_lshlrev_b32_e32 v80, 16, v74
	v_and_b32_e32 v81, 0xffff0000, v74
	v_lshlrev_b32_e32 v74, 16, v75
	v_and_b32_e32 v75, 0xffff0000, v75
	v_pk_add_f32 v[72:73], v[72:73], v[74:75]
	v_pk_add_f32 v[70:71], v[70:71], v[80:81]
	v_pk_add_f32 v[66:67], v[66:67], v[78:79]
	v_cvt_pk_bf16_f32 v70, v70, v71
	v_cvt_pk_bf16_f32 v71, v72, v73
	v_cvt_pk_bf16_f32 v72, v66, v67
	v_add_u32_e32 v66, 0x80, v156
	v_lshlrev_b32_e32 v76, 16, v77
	v_and_b32_e32 v77, 0xffff0000, v77
	v_ashrrev_i32_e32 v67, 31, v66
	v_pk_add_f32 v[68:69], v[68:69], v[76:77]
	v_lshlrev_b64 v[66:67], 10, v[66:67]
	v_cvt_pk_bf16_f32 v73, v68, v69
	v_lshl_add_u64 v[66:67], v[66:67], 0, v[154:155]
	global_store_dwordx4 v[82:83], v[70:73], off offset:256
	v_lshl_add_u64 v[66:67], v[66:67], 1, s[38:39]
	s_waitcnt vmcnt(14)
	v_mov_b64_e32 v[68:69], v[216:217]
	v_mov_b64_e32 v[70:71], v[218:219]
	s_nop 0
	v_lshlrev_b32_e32 v72, 16, v70
	v_and_b32_e32 v73, 0xffff0000, v70
	v_lshlrev_b32_e32 v70, 16, v71
	v_and_b32_e32 v71, 0xffff0000, v71
	v_lshlrev_b32_e32 v74, 16, v68
	v_and_b32_e32 v75, 0xffff0000, v68
	v_lshlrev_b32_e32 v68, 16, v69
	v_and_b32_e32 v69, 0xffff0000, v69
	v_pk_add_f32 v[64:65], v[64:65], v[68:69]
	v_pk_add_f32 v[62:63], v[62:63], v[74:75]
	v_pk_add_f32 v[60:61], v[60:61], v[70:71]
	v_pk_add_f32 v[58:59], v[58:59], v[72:73]
	v_cvt_pk_bf16_f32 v62, v62, v63
	v_cvt_pk_bf16_f32 v63, v64, v65
	v_cvt_pk_bf16_f32 v64, v58, v59
	v_cvt_pk_bf16_f32 v65, v60, v61
	s_waitcnt vmcnt(14)
	v_mov_b64_e32 v[58:59], v[220:221]
	v_mov_b64_e32 v[60:61], v[222:223]
	s_nop 0
	global_store_dwordx4 v[66:67], v[62:65], off
	s_nop 0
	s_nop 0
	v_lshlrev_b32_e32 v62, 16, v60
	v_and_b32_e32 v63, 0xffff0000, v60
	v_lshlrev_b32_e32 v64, 16, v58
	v_and_b32_e32 v65, 0xffff0000, v58
	v_lshlrev_b32_e32 v58, 16, v59
	v_and_b32_e32 v59, 0xffff0000, v59
	v_pk_add_f32 v[56:57], v[56:57], v[58:59]
	v_pk_add_f32 v[54:55], v[54:55], v[64:65]
	v_pk_add_f32 v[50:51], v[50:51], v[62:63]
	v_cvt_pk_bf16_f32 v54, v54, v55
	v_cvt_pk_bf16_f32 v55, v56, v57
	v_cvt_pk_bf16_f32 v56, v50, v51
	v_add_u32_e32 v50, 0x90, v156
	v_lshlrev_b32_e32 v60, 16, v61
	v_and_b32_e32 v61, 0xffff0000, v61
	v_ashrrev_i32_e32 v51, 31, v50
	v_pk_add_f32 v[52:53], v[52:53], v[60:61]
	v_lshlrev_b64 v[50:51], 10, v[50:51]
	v_cvt_pk_bf16_f32 v57, v52, v53
	v_lshl_add_u64 v[50:51], v[50:51], 0, v[154:155]
	global_store_dwordx4 v[66:67], v[54:57], off offset:256
	v_lshl_add_u64 v[50:51], v[50:51], 1, s[38:39]
	s_waitcnt vmcnt(14)
	v_mov_b64_e32 v[52:53], v[224:225]
	v_mov_b64_e32 v[54:55], v[226:227]
	s_nop 0
	v_lshlrev_b32_e32 v56, 16, v54
	v_and_b32_e32 v57, 0xffff0000, v54
	v_lshlrev_b32_e32 v54, 16, v55
	v_and_b32_e32 v55, 0xffff0000, v55
	v_lshlrev_b32_e32 v58, 16, v52
	v_and_b32_e32 v59, 0xffff0000, v52
	v_lshlrev_b32_e32 v52, 16, v53
	v_and_b32_e32 v53, 0xffff0000, v53
	v_pk_add_f32 v[48:49], v[48:49], v[52:53]
	v_pk_add_f32 v[46:47], v[46:47], v[58:59]
	v_pk_add_f32 v[44:45], v[44:45], v[54:55]
	v_pk_add_f32 v[42:43], v[42:43], v[56:57]
	v_cvt_pk_bf16_f32 v46, v46, v47
	v_cvt_pk_bf16_f32 v47, v48, v49
	v_cvt_pk_bf16_f32 v48, v42, v43
	v_cvt_pk_bf16_f32 v49, v44, v45
	s_waitcnt vmcnt(14)
	v_mov_b64_e32 v[42:43], v[228:229]
	v_mov_b64_e32 v[44:45], v[230:231]
	s_nop 0
	global_store_dwordx4 v[50:51], v[46:49], off
	s_nop 0
	s_nop 0
	v_lshlrev_b32_e32 v46, 16, v44
	v_and_b32_e32 v47, 0xffff0000, v44
	v_lshlrev_b32_e32 v48, 16, v42
	v_and_b32_e32 v49, 0xffff0000, v42
	v_lshlrev_b32_e32 v42, 16, v43
	v_and_b32_e32 v43, 0xffff0000, v43
	v_pk_add_f32 v[40:41], v[40:41], v[42:43]
	v_pk_add_f32 v[38:39], v[38:39], v[48:49]
	v_pk_add_f32 v[34:35], v[34:35], v[46:47]
	v_cvt_pk_bf16_f32 v38, v38, v39
	v_cvt_pk_bf16_f32 v39, v40, v41
	v_cvt_pk_bf16_f32 v40, v34, v35
	v_add_u32_e32 v34, 0xa0, v156
	v_lshlrev_b32_e32 v44, 16, v45
	v_and_b32_e32 v45, 0xffff0000, v45
	v_ashrrev_i32_e32 v35, 31, v34
	v_pk_add_f32 v[36:37], v[36:37], v[44:45]
	v_lshlrev_b64 v[34:35], 10, v[34:35]
	v_cvt_pk_bf16_f32 v41, v36, v37
	v_lshl_add_u64 v[34:35], v[34:35], 0, v[154:155]
	global_store_dwordx4 v[50:51], v[38:41], off offset:256
	v_lshl_add_u64 v[34:35], v[34:35], 1, s[38:39]
	s_waitcnt vmcnt(14)
	v_mov_b64_e32 v[36:37], v[232:233]
	v_mov_b64_e32 v[38:39], v[234:235]
	s_nop 0
	v_lshlrev_b32_e32 v40, 16, v38
	v_and_b32_e32 v41, 0xffff0000, v38
	v_lshlrev_b32_e32 v38, 16, v39
	v_and_b32_e32 v39, 0xffff0000, v39
	v_lshlrev_b32_e32 v42, 16, v36
	v_and_b32_e32 v43, 0xffff0000, v36
	v_lshlrev_b32_e32 v36, 16, v37
	v_and_b32_e32 v37, 0xffff0000, v37
	v_pk_add_f32 v[32:33], v[32:33], v[36:37]
	v_pk_add_f32 v[30:31], v[30:31], v[42:43]
	v_pk_add_f32 v[28:29], v[28:29], v[38:39]
	v_pk_add_f32 v[26:27], v[26:27], v[40:41]
	v_cvt_pk_bf16_f32 v30, v30, v31
	v_cvt_pk_bf16_f32 v31, v32, v33
	v_cvt_pk_bf16_f32 v32, v26, v27
	v_cvt_pk_bf16_f32 v33, v28, v29
	s_waitcnt vmcnt(14)
	v_mov_b64_e32 v[26:27], v[236:237]
	v_mov_b64_e32 v[28:29], v[238:239]
	s_nop 0
	global_store_dwordx4 v[34:35], v[30:33], off
	s_nop 0
	s_nop 0
	v_lshlrev_b32_e32 v30, 16, v28
	v_and_b32_e32 v31, 0xffff0000, v28
	v_lshlrev_b32_e32 v32, 16, v26
	v_and_b32_e32 v33, 0xffff0000, v26
	v_lshlrev_b32_e32 v26, 16, v27
	v_and_b32_e32 v27, 0xffff0000, v27
	v_pk_add_f32 v[24:25], v[24:25], v[26:27]
	v_pk_add_f32 v[22:23], v[22:23], v[32:33]
	v_pk_add_f32 v[18:19], v[18:19], v[30:31]
	v_cvt_pk_bf16_f32 v22, v22, v23
	v_cvt_pk_bf16_f32 v23, v24, v25
	v_cvt_pk_bf16_f32 v24, v18, v19
	v_add_u32_e32 v18, 0xb0, v156
	v_lshlrev_b32_e32 v28, 16, v29
	v_and_b32_e32 v29, 0xffff0000, v29
	v_ashrrev_i32_e32 v19, 31, v18
	v_pk_add_f32 v[20:21], v[20:21], v[28:29]
	v_lshlrev_b64 v[18:19], 10, v[18:19]
	v_cvt_pk_bf16_f32 v25, v20, v21
	v_lshl_add_u64 v[18:19], v[18:19], 0, v[154:155]
	global_store_dwordx4 v[34:35], v[22:25], off offset:256
	v_lshl_add_u64 v[18:19], v[18:19], 1, s[38:39]
	s_waitcnt vmcnt(14)
	v_mov_b64_e32 v[20:21], v[240:241]
	v_mov_b64_e32 v[22:23], v[242:243]
	s_nop 0
	v_lshlrev_b32_e32 v24, 16, v22
	v_and_b32_e32 v25, 0xffff0000, v22
	v_lshlrev_b32_e32 v22, 16, v23
	v_and_b32_e32 v23, 0xffff0000, v23
	v_lshlrev_b32_e32 v26, 16, v20
	v_and_b32_e32 v27, 0xffff0000, v20
	v_lshlrev_b32_e32 v20, 16, v21
	v_and_b32_e32 v21, 0xffff0000, v21
	v_pk_add_f32 v[16:17], v[16:17], v[20:21]
	v_pk_add_f32 v[14:15], v[14:15], v[26:27]
	v_pk_add_f32 v[12:13], v[12:13], v[22:23]
	v_pk_add_f32 v[10:11], v[10:11], v[24:25]
	v_cvt_pk_bf16_f32 v14, v14, v15
	v_cvt_pk_bf16_f32 v15, v16, v17
	v_cvt_pk_bf16_f32 v16, v10, v11
	v_cvt_pk_bf16_f32 v17, v12, v13
	s_waitcnt vmcnt(14)
	v_mov_b64_e32 v[10:11], v[244:245]
	v_mov_b64_e32 v[12:13], v[246:247]
	s_nop 0
	global_store_dwordx4 v[18:19], v[14:17], off
	s_nop 0
	s_nop 0
	v_lshlrev_b32_e32 v14, 16, v12
	v_and_b32_e32 v15, 0xffff0000, v12
	v_lshlrev_b32_e32 v12, 16, v13
	v_and_b32_e32 v13, 0xffff0000, v13
	v_lshlrev_b32_e32 v16, 16, v10
	v_and_b32_e32 v17, 0xffff0000, v10
	v_lshlrev_b32_e32 v10, 16, v11
	v_and_b32_e32 v11, 0xffff0000, v11
	v_pk_add_f32 v[8:9], v[8:9], v[10:11]
	v_pk_add_f32 v[6:7], v[6:7], v[16:17]
	v_pk_add_f32 v[4:5], v[4:5], v[12:13]
	v_pk_add_f32 v[2:3], v[2:3], v[14:15]
	v_cvt_pk_bf16_f32 v6, v6, v7
	v_cvt_pk_bf16_f32 v7, v8, v9
	v_cvt_pk_bf16_f32 v8, v2, v3
	v_cvt_pk_bf16_f32 v9, v4, v5
	global_store_dwordx4 v[18:19], v[6:9], off offset:256
